# v57 plus diff-attention item epilogue: sub-layer norm weights DMA'd to LDS once per phase and read with ds_read, so the 16 store steps no longer wait on loads and prior store acks
# speedup vs baseline: 1.0077x; 1.0060x over previous
; __device__ __forceinline__ unsigned xb_xcc_id() { return (unsigned)__builtin_amdgcn_s_getreg((3 << 11) | 20) & 0xFu; }
; #define ALDS __attribute__((address_space(3)))
; __device__ __forceinline__ ArgsP args_ptr() { ArgsP p = (ArgsP)__builtin_amdgcn_kernarg_segment_ptr(); asm volatile("" : "+s"(p)); return p; }
; #define TIDS() int lane_ = (int)__builtin_amdgcn_mbcnt_hi(~0u, __builtin_amdgcn_mbcnt_lo(~0u, 0u)); asm volatile("" : "+v"(lane_)); const int lane = lane_ & 63, wave = wave_s & 7, tid = wave * 64 + lane; const int G = gridDim.x, bx = blockIdx.x; (void)lane; (void)wave; (void)tid; (void)G; (void)bx
; __device__ __forceinline__ int diff_item(ldsp lds, int qt, int bh, bool pre, unsigned* nctr, const bf16* U, bf16* O, const float* subw, float lam, float omlinit, float M0, int wave, int lane) {
;     ...
;         const float* swp = subw; asm volatile("" : "+s"(swp));
; #pragma unroll
;         for (int et = 0; et < 4; ++et)
; #pragma unroll
;             for (int g4 = 0; g4 < 4; ++g4) { const int e0 = 32 * et + 8 * g4; const f32x4 w = *(const f32x4*)(swp + e0 + 4 * hh_e);
;     ArgsP a = args_ptr(); TIDS(); unsigned char* ws = a->ws; const int j = L >> 1; const bool diff = (L & 1) != 0;
;     att::ldsp lds = (att::ldsp)lds_;
;     ALDS unsigned* ctl = (ALDS unsigned*)(lds + att::CTL_OFF);
;     unsigned* ctr = (unsigned*)(ws + WS_CTL) + 64 * L + 8 * rep;
;     const bf16* U = (const bf16*)(ws + WS_U); bf16* O = (bf16*)(ws + WS_O); const bf16* MKVl = (const bf16*)(ws + WS_MKV) + (size_t)L * MEMR * 512;
;     float M0d = 0.f, lam = 0.f, omlinit = 0.f;
;     unsigned tk0 = 0u;
;     if (diff && tid == 0) tk0 = atomicAdd((unsigned*)(ws + WS_CTL) + 1024 + 512 * L + 4 * rep + 64 * (int)(xb_xcc_id() & 7u), 1u);
;     if (diff) {
;         const float mq = att::wave_max(fabsf(a->in[10][j * 64 + lane])), mk = att::wave_max(fabsf(a->in[11][j * 64 + lane]));
;         M0d = 8.0f * mq * mk * att::LOG2E * 1.05f;
;         const float linit = 0.8f - 0.6f * expf(-0.3f * (float)L);
;         const float d1 = wave_sum(a->in[12][j * 64 + lane] * a->in[13][j * 64 + lane]), d2 = wave_sum(a->in[14][j * 64 + lane] * a->in[15][j * 64 + lane]);
;         lam = expf(d1) - expf(d2) + linit; omlinit = 1.0f - linit;
;     }
;     const float* subw = a->in[16] + j * 128;
.LBB0_787:
	s_or_b64 exec, exec, s[10:11]
	s_mov_b64 s[46:47], s[96:97]
	s_waitcnt lgkmcnt(0)
	v_mov_b32_e32 v0, v201
	s_barrier
	s_load_dwordx2 s[98:99], s[46:47], 0x80
	v_and_b32_e32 v254, 63, v201
	v_lshlrev_b32_e32 v254, 4, v254
	s_mov_b64 exec, 0xffffffff
	s_mov_b32 m0, 0x20080
	s_waitcnt lgkmcnt(0)
	global_load_lds_dwordx4 v254, s[98:99]
	s_mov_b64 exec, -1
	s_load_dwordx2 s[44:45], s[46:47], 0xa8
	v_and_b32_e32 v152, 63, v0
	v_or_b32_e32 v1, s86, v152
	v_mov_b32_e32 v153, 0
	v_cmp_eq_u32_e64 s[12:13], 0, v1
	s_and_saveexec_b64 s[10:11], s[12:13]
	s_cbranch_execz .LBB0_791
	s_mov_b64 s[18:19], exec
	v_mbcnt_lo_u32_b32 v1, s18, 0
	v_mbcnt_hi_u32_b32 v1, s19, v1
	s_getreg_b32 s1, hwreg(HW_REG_XCC_ID, 0, 4)
	v_cmp_eq_u32_e32 vcc, 0, v1
	s_and_saveexec_b64 s[16:17], vcc
	s_cbranch_execz .LBB0_790
	s_lshl_b32 s1, s1, 8
	s_and_b32 s1, s1, 0x700
	s_waitcnt lgkmcnt(0)
	s_add_u32 s4, s44, s1
	s_addc_u32 s5, s45, 0
	s_bcnt1_i32_b64 s1, s[18:19]
	v_mov_b32_e32 v2, 0x1000
	v_mov_b32_e32 v3, s1
	global_atomic_add v2, v2, v3, s[4:5] offset:2048 sc0

; __device__ __forceinline__ unsigned xb_xcc_id() { return (unsigned)__builtin_amdgcn_s_getreg((3 << 11) | 20) & 0xFu; }
; #define ALDS __attribute__((address_space(3)))
; __device__ __forceinline__ ArgsP args_ptr() { ArgsP p = (ArgsP)__builtin_amdgcn_kernarg_segment_ptr(); asm volatile("" : "+s"(p)); return p; }
; #define TIDS() int lane_ = (int)__builtin_amdgcn_mbcnt_hi(~0u, __builtin_amdgcn_mbcnt_lo(~0u, 0u)); asm volatile("" : "+v"(lane_)); const int lane = lane_ & 63, wave = wave_s & 7, tid = wave * 64 + lane; const int G = gridDim.x, bx = blockIdx.x; (void)lane; (void)wave; (void)tid; (void)G; (void)bx
; __device__ __forceinline__ int diff_item(ldsp lds, int qt, int bh, bool pre, unsigned* nctr, const bf16* U, bf16* O, const float* subw, float lam, float omlinit, float M0, int wave, int lane) {
;     ...
;         const float* swp = subw; asm volatile("" : "+s"(swp));
; #pragma unroll
;         for (int et = 0; et < 4; ++et)
; #pragma unroll
;             for (int g4 = 0; g4 < 4; ++g4) { const int e0 = 32 * et + 8 * g4; const f32x4 w = *(const f32x4*)(swp + e0 + 4 * hh_e);
;     ArgsP a = args_ptr(); TIDS(); unsigned char* ws = a->ws; const int j = L >> 1; const bool diff = (L & 1) != 0;
;     att::ldsp lds = (att::ldsp)lds_;
;     ALDS unsigned* ctl = (ALDS unsigned*)(lds + att::CTL_OFF);
;     unsigned* ctr = (unsigned*)(ws + WS_CTL) + 64 * L + 8 * rep;
;     const bf16* U = (const bf16*)(ws + WS_U); bf16* O = (bf16*)(ws + WS_O); const bf16* MKVl = (const bf16*)(ws + WS_MKV) + (size_t)L * MEMR * 512;
;     float M0d = 0.f, lam = 0.f, omlinit = 0.f;
;     unsigned tk0 = 0u;
;     if (diff && tid == 0) tk0 = atomicAdd((unsigned*)(ws + WS_CTL) + 1024 + 512 * L + 4 * rep + 64 * (int)(xb_xcc_id() & 7u), 1u);
;     if (diff) {
;         const float mq = att::wave_max(fabsf(a->in[10][j * 64 + lane])), mk = att::wave_max(fabsf(a->in[11][j * 64 + lane]));
;         M0d = 8.0f * mq * mk * att::LOG2E * 1.05f;
;         const float linit = 0.8f - 0.6f * expf(-0.3f * (float)L);
;         const float d1 = wave_sum(a->in[12][j * 64 + lane] * a->in[13][j * 64 + lane]), d2 = wave_sum(a->in[14][j * 64 + lane] * a->in[15][j * 64 + lane]);
;         lam = expf(d1) - expf(d2) + linit; omlinit = 1.0f - linit;
;     }
;     const float* subw = a->in[16] + j * 128;
.LBB0_1831:
	s_or_b64 exec, exec, s[6:7]
	v_readlane_b32 s44, v252, 15
	v_readlane_b32 s45, v252, 16
	s_waitcnt lgkmcnt(0)
	v_mov_b32_e32 v0, v201
	s_barrier
	s_load_dwordx2 s[98:99], s[44:45], 0x80
	v_and_b32_e32 v254, 63, v201
	v_lshlrev_b32_e32 v254, 4, v254
	s_mov_b64 exec, 0xffffffff
	s_mov_b32 m0, 0x1fe80
	s_waitcnt lgkmcnt(0)
	global_load_lds_dwordx4 v254, s[98:99] offset:512
	s_mov_b64 exec, -1
	s_load_dwordx2 s[42:43], s[44:45], 0xa8
	v_and_b32_e32 v152, 63, v0
	v_readlane_b32 s0, v252, 1
	v_mov_b32_e32 v153, 0
	s_nop 0
	v_or_b32_e32 v1, s0, v152
	v_cmp_eq_u32_e64 s[6:7], 0, v1
	s_and_saveexec_b64 s[8:9], s[6:7]
	s_cbranch_execz .LBB0_1835
	s_mov_b64 s[16:17], exec
	v_mbcnt_lo_u32_b32 v1, s16, 0
	v_mbcnt_hi_u32_b32 v1, s17, v1
	s_getreg_b32 s0, hwreg(HW_REG_XCC_ID, 0, 4)
	v_cmp_eq_u32_e32 vcc, 0, v1
	s_and_saveexec_b64 s[14:15], vcc
	s_cbranch_execz .LBB0_1834
	s_lshl_b32 s0, s0, 8
	s_and_b32 s0, s0, 0x700
	s_waitcnt lgkmcnt(0)
	s_add_u32 s12, s42, s0
	s_addc_u32 s13, s43, 0
	s_bcnt1_i32_b64 s0, s[16:17]
	v_mov_b32_e32 v2, 0x2000
	v_mov_b32_e32 v3, s0
	global_atomic_add v2, v2, v3, s[12:13] offset:2048 sc0
